# t10 + nt added to the sc1 stores of the bf16 weight transposes (streamed, consumed a layer later)
# speedup vs baseline: 1.0018x; 1.0018x over previous
; __device__ __forceinline__ void tr_load(const TrItem& t, int lane, float (&v)[32]) {
;   const int nblk = t.N / 32, kb = t.item / nblk, nb = t.item % nblk, k0 = 64 * kb, n0 = 32 * nb;
;   const float* p = t.W + (size_t)(k0 + (lane >> 5)) * t.N + n0 + (lane & 31);
; #pragma unroll
;   for (int i = 0; i < 32; ++i) v[i] = __builtin_nontemporal_load(p + (size_t)(2 * i) * t.N);
; __global__ void __launch_bounds__(512) mega(Args a) {
;     ...
;           TR_DEC(it, T0) TR_DEC(h1 ? it + nwi : it, T1)
;           tr_load(T0, lane, v0); tr_load(T1, lane, v1);
.LBB0_117:
	s_or_b64 exec, exec, s[48:49]
	v_lshrrev_b32_e32 v18, 5, v25
	v_cvt_f32_u32_e32 v19, v18
	v_sub_u32_e32 v35, 0, v18
	v_sub_u32_e32 v34, 0, v3
	v_max_i32_e32 v34, v3, v34
	v_rcp_iflag_f32_e32 v19, v19
	v_ashrrev_i32_e32 v24, 31, v3
	v_lshlrev_b32_e32 v192, 3, v25
	v_lshlrev_b64 v[12:13], 1, v[12:13]
	v_mul_f32_e32 v19, 0x4f7ffffe, v19
	v_cvt_u32_f32_e32 v19, v19
	v_mul_lo_u32 v35, v35, v19
	v_mul_hi_u32 v35, v19, v35
	v_add_u32_e32 v19, v19, v35
	v_mul_hi_u32 v19, v34, v19
	v_mul_lo_u32 v35, v19, v18
	v_sub_u32_e32 v34, v34, v35
	v_add_u32_e32 v36, 1, v19
	v_sub_u32_e32 v35, v34, v18
	v_cmp_ge_u32_e64 s[0:1], v34, v18
	s_nop 1
	v_cndmask_b32_e64 v19, v19, v36, s[0:1]
	v_cndmask_b32_e64 v34, v34, v35, s[0:1]
	v_add_u32_e32 v35, 1, v19
	v_cmp_ge_u32_e64 s[0:1], v34, v18
	s_nop 1
	v_cndmask_b32_e64 v19, v19, v35, s[0:1]
	v_xor_b32_e32 v19, v19, v24
	v_sub_u32_e32 v19, v19, v24
	v_mul_lo_u32 v18, v19, v18
	v_lshlrev_b32_e32 v24, 6, v19
	v_sub_u32_e32 v3, v3, v18
	v_lshlrev_b32_e32 v18, 5, v3
	v_or_b32_e32 v3, v24, v26
	v_mad_i64_i32 v[34:35], s[0:1], v3, v25, 0
	v_lshl_add_u64 v[16:17], v[34:35], 2, v[16:17]
	v_ashrrev_i32_e32 v19, 31, v18
	v_lshl_add_u64 v[16:17], v[18:19], 2, v[16:17]
	v_mov_b32_e32 v3, v193
	v_lshl_add_u64 v[16:17], v[16:17], 0, v[2:3]
	v_lshl_add_u64 v[34:35], v[16:17], 0, v[192:193]
	v_lshl_add_u64 v[36:37], v[34:35], 0, v[192:193]
	v_lshl_add_u64 v[38:39], v[36:37], 0, v[192:193]
	v_lshl_add_u64 v[40:41], v[38:39], 0, v[192:193]
	v_lshl_add_u64 v[42:43], v[40:41], 0, v[192:193]
	v_lshl_add_u64 v[44:45], v[42:43], 0, v[192:193]
	v_lshl_add_u64 v[46:47], v[44:45], 0, v[192:193]
	global_load_dword v25, v[16:17], off nt
	global_load_dword v64, v[34:35], off nt
	global_load_dword v65, v[36:37], off nt
	global_load_dword v66, v[38:39], off nt
	global_load_dword v67, v[40:41], off nt
	global_load_dword v68, v[42:43], off nt
	global_load_dword v69, v[44:45], off nt
	global_load_dword v70, v[46:47], off nt
	v_lshl_add_u64 v[16:17], v[46:47], 0, v[192:193]
	global_load_dword v71, v[16:17], off nt
	v_lshl_add_u64 v[16:17], v[16:17], 0, v[192:193]
	global_load_dword v72, v[16:17], off nt
	v_lshl_add_u64 v[16:17], v[16:17], 0, v[192:193]
	global_load_dword v73, v[16:17], off nt
	v_lshl_add_u64 v[16:17], v[16:17], 0, v[192:193]
	global_load_dword v74, v[16:17], off nt
	v_lshl_add_u64 v[16:17], v[16:17], 0, v[192:193]
	global_load_dword v75, v[16:17], off nt
	v_lshl_add_u64 v[16:17], v[16:17], 0, v[192:193]
	global_load_dword v76, v[16:17], off nt
	v_lshl_add_u64 v[16:17], v[16:17], 0, v[192:193]
	global_load_dword v77, v[16:17], off nt
	v_lshl_add_u64 v[16:17], v[16:17], 0, v[192:193]
	global_load_dword v78, v[16:17], off nt
	v_lshl_add_u64 v[16:17], v[16:17], 0, v[192:193]
	global_load_dword v79, v[16:17], off nt
	v_lshl_add_u64 v[16:17], v[16:17], 0, v[192:193]
	global_load_dword v80, v[16:17], off nt
	v_lshl_add_u64 v[16:17], v[16:17], 0, v[192:193]
	global_load_dword v81, v[16:17], off nt
	v_lshl_add_u64 v[16:17], v[16:17], 0, v[192:193]
	global_load_dword v82, v[16:17], off nt
	v_lshl_add_u64 v[16:17], v[16:17], 0, v[192:193]
	global_load_dword v83, v[16:17], off nt
	v_lshl_add_u64 v[16:17], v[16:17], 0, v[192:193]
	global_load_dword v84, v[16:17], off nt
	v_lshl_add_u64 v[16:17], v[16:17], 0, v[192:193]
	global_load_dword v85, v[16:17], off nt
	v_lshl_add_u64 v[16:17], v[16:17], 0, v[192:193]
	v_lshrrev_b32_e32 v34, 5, v23
	global_load_dword v86, v[16:17], off nt
	v_lshl_add_u64 v[16:17], v[16:17], 0, v[192:193]
	v_cvt_f32_u32_e32 v35, v34
	global_load_dword v87, v[16:17], off nt
	v_lshl_add_u64 v[16:17], v[16:17], 0, v[192:193]
	global_load_dword v88, v[16:17], off nt
	v_lshl_add_u64 v[16:17], v[16:17], 0, v[192:193]
	global_load_dword v89, v[16:17], off nt
	v_lshl_add_u64 v[16:17], v[16:17], 0, v[192:193]
	global_load_dword v90, v[16:17], off nt
	v_lshl_add_u64 v[16:17], v[16:17], 0, v[192:193]
	v_rcp_iflag_f32_e32 v35, v35
	global_load_dword v91, v[16:17], off nt
	v_lshl_add_u64 v[16:17], v[16:17], 0, v[192:193]
	global_load_dword v92, v[16:17], off nt
	v_lshl_add_u64 v[16:17], v[16:17], 0, v[192:193]
	global_load_dword v93, v[16:17], off nt
	v_lshl_add_u64 v[16:17], v[16:17], 0, v[192:193]
	global_load_dword v94, v[16:17], off nt
	v_mul_f32_e32 v17, 0x4f7ffffe, v35
	v_cvt_u32_f32_e32 v17, v17
	v_sub_u32_e32 v36, 0, v34
	v_sub_u32_e32 v35, 0, v22
	v_max_i32_e32 v35, v22, v35
	v_mul_lo_u32 v36, v36, v17
	v_mul_hi_u32 v36, v17, v36
	v_add_u32_e32 v17, v17, v36
	v_mul_hi_u32 v17, v35, v17
	v_mul_lo_u32 v36, v17, v34
	v_sub_u32_e32 v35, v35, v36
	v_add_u32_e32 v36, 1, v17
	v_cmp_ge_u32_e64 s[0:1], v35, v34
	v_ashrrev_i32_e32 v16, 31, v22
	v_lshlrev_b32_e32 v192, 3, v23
	v_cndmask_b32_e64 v17, v17, v36, s[0:1]
	v_sub_u32_e32 v36, v35, v34
	v_cndmask_b32_e64 v35, v35, v36, s[0:1]
	v_add_u32_e32 v36, 1, v17
	v_cmp_ge_u32_e64 s[0:1], v35, v34
	v_mul_lo_u32 v19, v8, v19
	s_nop 0
	v_cndmask_b32_e64 v17, v17, v36, s[0:1]
	v_xor_b32_e32 v17, v17, v16
	v_sub_u32_e32 v16, v17, v16
	v_mul_lo_u32 v17, v16, v34
	v_sub_u32_e32 v17, v22, v17
	v_lshlrev_b32_e32 v22, 6, v16
	v_lshlrev_b32_e32 v16, 5, v17
	v_or_b32_e32 v17, v22, v26
	v_mad_i64_i32 v[34:35], s[0:1], v17, v23, 0
	v_lshl_add_u64 v[20:21], v[34:35], 2, v[20:21]
	v_ashrrev_i32_e32 v17, 31, v16
	v_lshl_add_u64 v[20:21], v[16:17], 2, v[20:21]
	v_lshl_add_u64 v[20:21], v[20:21], 0, v[2:3]
	v_lshl_add_u64 v[34:35], v[20:21], 0, v[192:193]
	v_lshl_add_u64 v[36:37], v[34:35], 0, v[192:193]
	v_lshl_add_u64 v[38:39], v[36:37], 0, v[192:193]
	v_lshl_add_u64 v[40:41], v[38:39], 0, v[192:193]
	v_lshl_add_u64 v[42:43], v[40:41], 0, v[192:193]
	v_lshl_add_u64 v[44:45], v[42:43], 0, v[192:193]
; #define LAS __attribute__((address_space(3)))
; __device__ __forceinline__ unsigned cvt_pk_bf16(float lo, float hi) { f32x2_t v = {lo, hi}; bf16x2_t r = __builtin_convertvector(v, bf16x2_t); return __builtin_bit_cast(unsigned, r); }
; __device__ __forceinline__ void tr_load(const TrItem& t, int lane, float (&v)[32]) {
;     ...
;   for (int i = 0; i < 32; ++i) v[i] = __builtin_nontemporal_load(p + (size_t)(2 * i) * t.N);
; }
; __device__ __forceinline__ void tr_finish(const TrItem& t, int lane, const float (&v)[32], LAS float* scr) {
;   const int nblk = t.N / 32, kb = t.item / nblk, nb = t.item % nblk, k0 = 64 * kb, n0 = 32 * nb;
; #pragma unroll
;   for (int i = 0; i < 32; ++i) scr[(2 * i + (lane >> 5)) * 33 + (lane & 31)] = v[i];
;   asm volatile("s_waitcnt lgkmcnt(0)" ::: "memory");
;   const int c = lane & 7;
; #pragma unroll
;   for (int j = 0; j < 4; ++j) { const int n = (lane >> 3) + 8 * j; const LAS float* sp = scr + (8 * c) * 33 + n;
;     u32x4 o; o.x = cvt_pk_bf16(sp[0 * 33], sp[1 * 33]); o.y = cvt_pk_bf16(sp[2 * 33], sp[3 * 33]); o.z = cvt_pk_bf16(sp[4 * 33], sp[5 * 33]); o.w = cvt_pk_bf16(sp[6 * 33], sp[7 * 33]);
;     *(u32x4*)(t.WT + (size_t)(n0 + n) * t.ldt + t.koff + k0 + 8 * c) = o; }
	v_lshl_add_u64 v[46:47], v[44:45], 0, v[192:193]
	global_load_dword v3, v[20:21], off nt
	s_nop 0
	global_load_dword v20, v[34:35], off nt
	global_load_dword v21, v[36:37], off nt
	global_load_dword v23, v[38:39], off nt
	s_nop 0
	global_load_dword v34, v[40:41], off nt
	global_load_dword v35, v[42:43], off nt
	global_load_dword v36, v[44:45], off nt
	global_load_dword v37, v[46:47], off nt
	v_lshl_add_u64 v[40:41], v[46:47], 0, v[192:193]
	global_load_dword v38, v[40:41], off nt
	v_lshl_add_u64 v[40:41], v[40:41], 0, v[192:193]
	v_lshl_add_u64 v[42:43], v[40:41], 0, v[192:193]
	global_load_dword v39, v[40:41], off nt
	s_nop 0
	global_load_dword v40, v[42:43], off nt
	v_lshl_add_u64 v[42:43], v[42:43], 0, v[192:193]
	v_lshl_add_u64 v[44:45], v[42:43], 0, v[192:193]
	global_load_dword v41, v[42:43], off nt
	s_nop 0
	global_load_dword v42, v[44:45], off nt
	v_lshl_add_u64 v[44:45], v[44:45], 0, v[192:193]
	v_lshl_add_u64 v[46:47], v[44:45], 0, v[192:193]
	global_load_dword v43, v[44:45], off nt
	s_nop 0
	global_load_dword v44, v[46:47], off nt
	v_lshl_add_u64 v[46:47], v[46:47], 0, v[192:193]
	v_lshl_add_u64 v[48:49], v[46:47], 0, v[192:193]
	global_load_dword v45, v[46:47], off nt
	s_nop 0
	global_load_dword v46, v[48:49], off nt
	v_lshl_add_u64 v[48:49], v[48:49], 0, v[192:193]
	v_lshl_add_u64 v[50:51], v[48:49], 0, v[192:193]
	global_load_dword v47, v[48:49], off nt
	s_nop 0
	global_load_dword v48, v[50:51], off nt
	v_lshl_add_u64 v[50:51], v[50:51], 0, v[192:193]
	v_lshl_add_u64 v[52:53], v[50:51], 0, v[192:193]
	global_load_dword v49, v[50:51], off nt
	s_nop 0
	global_load_dword v50, v[52:53], off nt
	v_lshl_add_u64 v[52:53], v[52:53], 0, v[192:193]
	v_lshl_add_u64 v[54:55], v[52:53], 0, v[192:193]
	global_load_dword v51, v[52:53], off nt
	s_nop 0
	global_load_dword v52, v[54:55], off nt
	v_lshl_add_u64 v[54:55], v[54:55], 0, v[192:193]
	v_lshl_add_u64 v[56:57], v[54:55], 0, v[192:193]
	global_load_dword v53, v[54:55], off nt
	s_nop 0
	global_load_dword v54, v[56:57], off nt
	v_lshl_add_u64 v[56:57], v[56:57], 0, v[192:193]
	v_lshl_add_u64 v[58:59], v[56:57], 0, v[192:193]
	global_load_dword v55, v[56:57], off nt
	s_nop 0
	global_load_dword v56, v[58:59], off nt
	v_lshl_add_u64 v[58:59], v[58:59], 0, v[192:193]
	v_lshl_add_u64 v[60:61], v[58:59], 0, v[192:193]
	global_load_dword v57, v[58:59], off nt
	s_nop 0
	global_load_dword v58, v[60:61], off nt
	v_lshl_add_u64 v[60:61], v[60:61], 0, v[192:193]
	v_lshl_add_u64 v[62:63], v[60:61], 0, v[192:193]
	global_load_dword v59, v[60:61], off nt
	s_nop 0
	global_load_dword v60, v[62:63], off nt
	v_lshl_add_u64 v[62:63], v[62:63], 0, v[192:193]
	global_load_dword v61, v[62:63], off nt
	v_add_u32_e32 v62, 0x400, v33
	s_waitcnt vmcnt(62)
	ds_write2_b32 v33, v25, v64 offset1:66
	s_waitcnt vmcnt(60)
	ds_write2_b32 v33, v65, v66 offset0:132 offset1:198
	s_waitcnt vmcnt(58)
	ds_write2_b32 v62, v67, v68 offset0:8 offset1:74
	s_waitcnt vmcnt(56)
	ds_write2_b32 v62, v69, v70 offset0:140 offset1:206
	v_add_u32_e32 v63, 0x800, v33
	v_add_u32_e32 v64, 0xc00, v33
	v_add_u32_e32 v65, 0x1000, v33
	v_add_u32_e32 v66, 0x1400, v33
	v_add_u32_e32 v67, 0x1800, v33
	v_add_u32_e32 v68, 0x1c00, v33
	s_waitcnt vmcnt(54)
	ds_write2_b32 v63, v71, v72 offset0:16 offset1:82
	s_waitcnt vmcnt(52)
	ds_write2_b32 v63, v73, v74 offset0:148 offset1:214
	s_waitcnt vmcnt(50)
	ds_write2_b32 v64, v75, v76 offset0:24 offset1:90
	s_waitcnt vmcnt(48)
	ds_write2_b32 v64, v77, v78 offset0:156 offset1:222
	s_waitcnt vmcnt(46)
	ds_write2_b32 v65, v79, v80 offset0:32 offset1:98
	s_waitcnt vmcnt(44)
	ds_write2_b32 v65, v81, v82 offset0:164 offset1:230
	s_waitcnt vmcnt(42)
	ds_write2_b32 v66, v83, v84 offset0:40 offset1:106
	s_waitcnt vmcnt(40)
	ds_write2_b32 v66, v85, v86 offset0:172 offset1:238
	s_waitcnt vmcnt(38)
	ds_write2_b32 v67, v87, v88 offset0:48 offset1:114
	s_waitcnt vmcnt(36)
	ds_write2_b32 v67, v89, v90 offset0:180 offset1:246
	s_waitcnt vmcnt(34)
	ds_write2_b32 v68, v91, v92 offset0:56 offset1:122
	s_waitcnt vmcnt(32)
	ds_write2_b32 v68, v93, v94 offset0:188 offset1:254
	s_waitcnt lgkmcnt(0)
	ds_read2_b32 v[74:75], v28 offset0:33 offset1:41
	ds_read2_b32 v[76:77], v28 offset1:8
	ds_read2_b32 v[78:79], v28 offset0:66 offset1:74
	ds_read2_b32 v[80:81], v28 offset0:99 offset1:107
	ds_read2_b32 v[82:83], v28 offset0:132 offset1:140
	ds_read2_b32 v[84:85], v28 offset0:165 offset1:173
	ds_read2_b32 v[86:87], v28 offset0:198 offset1:206
	ds_read2_b32 v[88:89], v28 offset0:231 offset1:239
	v_or_b32_e32 v69, v18, v27
	s_waitcnt lgkmcnt(6)
	v_cvt_pk_bf16_f32 v70, v76, v74
	v_mul_lo_u32 v74, v9, v69
	v_mad_u64_u32 v[90:91], s[0:1], v8, v69, 0
	v_add3_u32 v91, v91, v19, v74
	v_ashrrev_i32_e32 v25, 31, v24
	v_lshl_add_u64 v[90:91], v[90:91], 1, v[10:11]
	v_lshl_add_u64 v[90:91], v[90:91], 0, v[12:13]
	v_lshlrev_b64 v[24:25], 1, v[24:25]
	v_lshl_add_u64 v[90:91], v[90:91], 0, v[24:25]
	v_lshlrev_b32_e32 v192, 1, v0
	s_waitcnt lgkmcnt(4)
	v_cvt_pk_bf16_f32 v71, v78, v80
	s_waitcnt lgkmcnt(2)
	v_cvt_pk_bf16_f32 v72, v82, v84
	s_waitcnt lgkmcnt(0)
	v_cvt_pk_bf16_f32 v73, v86, v88
	v_lshl_add_u64 v[90:91], v[90:91], 0, v[192:193]
	v_or_b32_e32 v69, v18, v29
	global_store_dwordx4 v[90:91], v[70:73], off sc1 nt
	v_mul_lo_u32 v76, v9, v69
	s_nop 0
	v_cvt_pk_bf16_f32 v70, v77, v75
	v_mad_u64_u32 v[74:75], s[0:1], v8, v69, 0
	v_add3_u32 v75, v75, v19, v76
	v_lshl_add_u64 v[74:75], v[74:75], 1, v[10:11]
	v_lshl_add_u64 v[74:75], v[74:75], 0, v[12:13]
	v_lshl_add_u64 v[74:75], v[74:75], 0, v[24:25]
	v_cvt_pk_bf16_f32 v71, v79, v81
	v_cvt_pk_bf16_f32 v72, v83, v85
	v_cvt_pk_bf16_f32 v73, v87, v89
	v_lshl_add_u64 v[74:75], v[74:75], 0, v[192:193]
	ds_read2_b32 v[76:77], v28 offset0:16 offset1:24
	ds_read2_b32 v[78:79], v28 offset0:49 offset1:57
	ds_read2_b32 v[80:81], v28 offset0:82 offset1:90
	ds_read2_b32 v[82:83], v28 offset0:115 offset1:123
	ds_read2_b32 v[84:85], v28 offset0:148 offset1:156
	ds_read2_b32 v[86:87], v28 offset0:181 offset1:189
	ds_read2_b32 v[88:89], v28 offset0:214 offset1:222
	ds_read2_b32 v[90:91], v28 offset0:247 offset1:255
	v_or_b32_e32 v69, v18, v30
	global_store_dwordx4 v[74:75], v[70:73], off sc1 nt
	v_mad_u64_u32 v[74:75], s[0:1], v8, v69, 0
	s_waitcnt lgkmcnt(6)
; #define LAS __attribute__((address_space(3)))
; __device__ __forceinline__ unsigned cvt_pk_bf16(float lo, float hi) { f32x2_t v = {lo, hi}; bf16x2_t r = __builtin_convertvector(v, bf16x2_t); return __builtin_bit_cast(unsigned, r); }
; __device__ __forceinline__ void tr_finish(const TrItem& t, int lane, const float (&v)[32], LAS float* scr) {
;     ...
;   for (int i = 0; i < 32; ++i) scr[(2 * i + (lane >> 5)) * 33 + (lane & 31)] = v[i];
;   asm volatile("s_waitcnt lgkmcnt(0)" ::: "memory");
;   const int c = lane & 7;
; #pragma unroll
;   for (int j = 0; j < 4; ++j) { const int n = (lane >> 3) + 8 * j; const LAS float* sp = scr + (8 * c) * 33 + n;
;     u32x4 o; o.x = cvt_pk_bf16(sp[0 * 33], sp[1 * 33]); o.y = cvt_pk_bf16(sp[2 * 33], sp[3 * 33]); o.z = cvt_pk_bf16(sp[4 * 33], sp[5 * 33]); o.w = cvt_pk_bf16(sp[6 * 33], sp[7 * 33]);
;     *(u32x4*)(t.WT + (size_t)(n0 + n) * t.ldt + t.koff + k0 + 8 * c) = o; }
; __global__ void __launch_bounds__(512) mega(Args a) {
;     ...
;           tr_finish(T0, lane, v0, scr);
;           if (h1) tr_finish(T1, lane, v1, scr);
	v_cvt_pk_bf16_f32 v70, v76, v78
	v_mul_lo_u32 v76, v9, v69
	v_or_b32_e32 v18, v18, v31
	v_add3_u32 v75, v75, v19, v76
	v_mul_lo_u32 v69, v9, v18
	v_mad_u64_u32 v[8:9], s[0:1], v8, v18, 0
	v_lshl_add_u64 v[74:75], v[74:75], 1, v[10:11]
	v_add3_u32 v9, v9, v19, v69
	v_lshl_add_u64 v[74:75], v[74:75], 0, v[12:13]
	v_lshl_add_u64 v[8:9], v[8:9], 1, v[10:11]
	v_lshl_add_u64 v[74:75], v[74:75], 0, v[24:25]
	v_lshl_add_u64 v[8:9], v[8:9], 0, v[12:13]
	s_waitcnt lgkmcnt(4)
	v_cvt_pk_bf16_f32 v71, v80, v82
	s_waitcnt lgkmcnt(2)
	v_cvt_pk_bf16_f32 v72, v84, v86
	s_waitcnt lgkmcnt(0)
	v_cvt_pk_bf16_f32 v73, v88, v90
	v_lshl_add_u64 v[74:75], v[74:75], 0, v[192:193]
	v_lshl_add_u64 v[8:9], v[8:9], 0, v[24:25]
	global_store_dwordx4 v[74:75], v[70:73], off sc1 nt
	v_lshl_add_u64 v[8:9], v[8:9], 0, v[192:193]
	s_nop 0
	v_cvt_pk_bf16_f32 v70, v77, v79
	v_cvt_pk_bf16_f32 v71, v81, v83
	v_cvt_pk_bf16_f32 v72, v85, v87
	v_cvt_pk_bf16_f32 v73, v89, v91
	global_store_dwordx4 v[8:9], v[70:73], off sc1 nt
	s_waitcnt lgkmcnt(0)
	s_and_saveexec_b64 s[0:1], vcc
	s_cbranch_execz .LBB0_88
	s_waitcnt vmcnt(34)
	ds_write2_b32 v33, v3, v20 offset1:66
	s_waitcnt vmcnt(32)
	ds_write2_b32 v33, v21, v23 offset0:132 offset1:198
	s_waitcnt vmcnt(30)
	ds_write2_b32 v62, v34, v35 offset0:8 offset1:74
	s_waitcnt vmcnt(28)
	ds_write2_b32 v62, v36, v37 offset0:140 offset1:206
	s_waitcnt vmcnt(26)
	ds_write2_b32 v63, v38, v39 offset0:16 offset1:82
	s_waitcnt vmcnt(24)
	ds_write2_b32 v63, v40, v41 offset0:148 offset1:214
	s_waitcnt vmcnt(22)
	ds_write2_b32 v64, v42, v43 offset0:24 offset1:90
	s_waitcnt vmcnt(20)
	ds_write2_b32 v64, v44, v45 offset0:156 offset1:222
	s_waitcnt vmcnt(18)
	ds_write2_b32 v65, v46, v47 offset0:32 offset1:98
	s_waitcnt vmcnt(16)
	ds_write2_b32 v65, v48, v49 offset0:164 offset1:230
	s_waitcnt vmcnt(14)
	ds_write2_b32 v66, v50, v51 offset0:40 offset1:106
	s_waitcnt vmcnt(12)
	ds_write2_b32 v66, v52, v53 offset0:172 offset1:238
	s_waitcnt vmcnt(10)
	ds_write2_b32 v67, v54, v55 offset0:48 offset1:114
	s_waitcnt vmcnt(8)
	ds_write2_b32 v67, v56, v57 offset0:180 offset1:246
	s_waitcnt vmcnt(6)
	ds_write2_b32 v68, v58, v59 offset0:56 offset1:122
	s_waitcnt vmcnt(4)
	ds_write2_b32 v68, v60, v61 offset0:188 offset1:254
	s_waitcnt lgkmcnt(0)
	ds_read2_b32 v[12:13], v28 offset0:33 offset1:41
	ds_read2_b32 v[18:19], v28 offset1:8
	ds_read2_b32 v[20:21], v28 offset0:66 offset1:74
	ds_read2_b32 v[24:25], v28 offset0:99 offset1:107
	ds_read2_b32 v[34:35], v28 offset0:132 offset1:140
	ds_read2_b32 v[36:37], v28 offset0:165 offset1:173
	ds_read2_b32 v[38:39], v28 offset0:198 offset1:206
	ds_read2_b32 v[40:41], v28 offset0:231 offset1:239
	v_or_b32_e32 v3, v16, v27
	s_waitcnt lgkmcnt(6)
	v_cvt_pk_bf16_f32 v8, v18, v12
	v_mul_lo_u32 v12, v5, v3
	v_mul_lo_u32 v17, v4, v17
	v_mad_u64_u32 v[42:43], s[22:23], v4, v3, 0
	v_add3_u32 v43, v43, v17, v12
	v_ashrrev_i32_e32 v23, 31, v22
	v_lshl_add_u64 v[42:43], v[42:43], 1, v[14:15]
	v_lshlrev_b64 v[44:45], 1, v[6:7]
	v_lshl_add_u64 v[6:7], v[42:43], 0, v[44:45]
	v_lshlrev_b64 v[22:23], 1, v[22:23]
	v_lshl_add_u64 v[6:7], v[6:7], 0, v[22:23]
	s_waitcnt lgkmcnt(4)
	v_cvt_pk_bf16_f32 v9, v20, v24
	s_waitcnt lgkmcnt(2)
	v_cvt_pk_bf16_f32 v10, v34, v36
	s_waitcnt lgkmcnt(0)
	v_cvt_pk_bf16_f32 v11, v38, v40
	v_lshl_add_u64 v[6:7], v[6:7], 0, v[192:193]
	v_or_b32_e32 v3, v16, v29
	global_store_dwordx4 v[6:7], v[8:11], off sc1 nt
	v_mul_lo_u32 v12, v5, v3
	v_cvt_pk_bf16_f32 v6, v19, v13
	v_mad_u64_u32 v[10:11], s[22:23], v4, v3, 0
	v_add3_u32 v11, v11, v17, v12
	v_lshl_add_u64 v[10:11], v[10:11], 1, v[14:15]
	v_lshl_add_u64 v[10:11], v[10:11], 0, v[44:45]
	v_lshl_add_u64 v[10:11], v[10:11], 0, v[22:23]
	v_cvt_pk_bf16_f32 v7, v21, v25
	v_cvt_pk_bf16_f32 v8, v35, v37
	v_cvt_pk_bf16_f32 v9, v39, v41
	v_lshl_add_u64 v[10:11], v[10:11], 0, v[192:193]
	ds_read2_b32 v[12:13], v28 offset0:16 offset1:24
	ds_read2_b32 v[18:19], v28 offset0:49 offset1:57
	ds_read2_b32 v[20:21], v28 offset0:82 offset1:90
	ds_read2_b32 v[24:25], v28 offset0:115 offset1:123
	ds_read2_b32 v[34:35], v28 offset0:148 offset1:156
	ds_read2_b32 v[36:37], v28 offset0:181 offset1:189
	ds_read2_b32 v[38:39], v28 offset0:214 offset1:222
	ds_read2_b32 v[40:41], v28 offset0:247 offset1:255
	v_or_b32_e32 v3, v16, v30
	global_store_dwordx4 v[10:11], v[6:9], off sc1 nt
	v_mad_u64_u32 v[10:11], s[22:23], v4, v3, 0
	s_waitcnt lgkmcnt(6)
	v_cvt_pk_bf16_f32 v6, v12, v18
	v_mul_lo_u32 v12, v5, v3
	v_add3_u32 v11, v11, v17, v12
	v_lshl_add_u64 v[10:11], v[10:11], 1, v[14:15]
	v_lshl_add_u64 v[10:11], v[10:11], 0, v[44:45]
	v_lshl_add_u64 v[10:11], v[10:11], 0, v[22:23]
	s_waitcnt lgkmcnt(4)
	v_cvt_pk_bf16_f32 v7, v20, v24
	s_waitcnt lgkmcnt(2)
	v_cvt_pk_bf16_f32 v8, v34, v36
	s_waitcnt lgkmcnt(0)
	v_cvt_pk_bf16_f32 v9, v38, v40
	v_lshl_add_u64 v[10:11], v[10:11], 0, v[192:193]
	v_or_b32_e32 v3, v16, v31
	global_store_dwordx4 v[10:11], v[6:9], off sc1 nt
	v_mul_lo_u32 v10, v5, v3
	v_mad_u64_u32 v[4:5], s[22:23], v4, v3, 0
	v_add3_u32 v5, v5, v17, v10
	v_lshl_add_u64 v[4:5], v[4:5], 1, v[14:15]
	v_lshl_add_u64 v[4:5], v[4:5], 0, v[44:45]
	v_lshl_add_u64 v[4:5], v[4:5], 0, v[22:23]
	v_cvt_pk_bf16_f32 v6, v13, v19
	v_cvt_pk_bf16_f32 v7, v21, v25
	v_cvt_pk_bf16_f32 v8, v35, v37
	v_cvt_pk_bf16_f32 v9, v39, v41
	v_lshl_add_u64 v[4:5], v[4:5], 0, v[192:193]
	global_store_dwordx4 v[4:5], v[6:9], off sc1 nt
	s_waitcnt lgkmcnt(0)
	s_branch .LBB0_88
